# K-loop: seg-5 B-operand ds_reads hoisted into MFMA block 4 (after vmcnt(6)+barrier), interleaved with first 4 MFMAs
# baseline (speedup 1.0000x reference)
.LBB0_744:
	s_add_i32 s44, s4, 2
	s_add_u32 s8, s6, 0x80
	s_addc_u32 s5, s7, 0
	s_add_i32 s45, 0, 0x10000
	v_add_u32_e32 v140, s45, v234
	ds_read_b128 v[128:131], v140
	ds_read_b128 v[132:135], v140 offset:1024
	ds_read_b128 v[136:139], v140 offset:2048
	ds_read_b128 v[140:143], v140 offset:3072
	s_cmp_eq_u32 s27, s4
	s_cselect_b32 s4, s90, s8
	s_cselect_b32 s5, s91, s5
	s_cselect_b32 s9, s93, s43
	s_cselect_b32 s8, s92, s42
	v_lshl_add_u64 v[214:215], s[6:7], 0, v[206:207]
	s_add_i32 m0, s74, 0xc000
	ds_read_b128 v[144:147], v235
	ds_read_b128 v[148:151], v235 offset:1024
	ds_read_b128 v[152:155], v235 offset:2048
	ds_read_b128 v[156:159], v235 offset:3072
	ds_read_b128 v[160:163], v235 offset:4096
	ds_read_b128 v[164:167], v235 offset:5120
	ds_read_b128 v[168:171], v235 offset:6144
	ds_read_b128 v[210:213], v235 offset:7168
	global_load_lds_dwordx4 v[214:215], off
	v_lshl_add_u64 v[214:215], s[6:7], 0, v[208:209]
	s_add_i32 m0, s74, 0xe000
	s_nop 0
	global_load_lds_dwordx4 v[214:215], off
	s_waitcnt lgkmcnt(8)
	s_barrier
	s_waitcnt lgkmcnt(0)
	s_waitcnt lgkmcnt(0)
	v_mfma_f32_16x16x32_bf16 v[108:111], v[128:131], v[144:147], v[108:111]
	v_mfma_f32_16x16x32_bf16 v[104:107], v[136:139], v[144:147], v[104:107]
	v_mfma_f32_16x16x32_bf16 v[92:95], v[128:131], v[152:155], v[92:95]
	v_mfma_f32_16x16x32_bf16 v[80:83], v[136:139], v[152:155], v[80:83]
	v_mfma_f32_16x16x32_bf16 v[68:71], v[128:131], v[160:163], v[68:71]
	v_mfma_f32_16x16x32_bf16 v[56:59], v[136:139], v[160:163], v[56:59]
	v_mfma_f32_16x16x32_bf16 v[44:47], v[128:131], v[168:171], v[44:47]
	v_mfma_f32_16x16x32_bf16 v[32:35], v[136:139], v[168:171], v[32:35]
	v_mfma_f32_16x16x32_bf16 v[108:111], v[132:135], v[148:151], v[108:111]
	v_mfma_f32_16x16x32_bf16 v[104:107], v[140:143], v[148:151], v[104:107]
	v_mfma_f32_16x16x32_bf16 v[92:95], v[132:135], v[156:159], v[92:95]
	v_mfma_f32_16x16x32_bf16 v[80:83], v[140:143], v[156:159], v[80:83]
	v_mfma_f32_16x16x32_bf16 v[68:71], v[132:135], v[164:167], v[68:71]
	v_mfma_f32_16x16x32_bf16 v[56:59], v[140:143], v[164:167], v[56:59]
	v_mfma_f32_16x16x32_bf16 v[44:47], v[132:135], v[210:213], v[44:47]
	v_mfma_f32_16x16x32_bf16 v[32:35], v[140:143], v[210:213], v[32:35]
	s_barrier
	s_add_i32 s45, s45, s97
	v_add_u32_e32 v172, s3, v234
	v_lshl_add_u64 v[244:245], s[8:9], 0, v[184:185]
	s_mov_b32 m0, s45
	ds_read_b128 v[214:217], v172
	ds_read_b128 v[218:221], v172 offset:1024
	ds_read_b128 v[236:239], v172 offset:2048
	ds_read_b128 v[240:243], v172 offset:3072
	global_load_lds_dwordx4 v[244:245], off
	v_lshl_add_u64 v[246:247], s[8:9], 0, v[188:189]
	s_add_i32 m0, s45, 0x2000
	s_nop 0
	global_load_lds_dwordx4 v[246:247], off
	s_barrier
	s_waitcnt lgkmcnt(0)
	s_waitcnt lgkmcnt(0)
	v_mfma_f32_16x16x32_bf16 v[124:127], v[214:217], v[144:147], v[124:127]
	v_mfma_f32_16x16x32_bf16 v[120:123], v[236:239], v[144:147], v[120:123]
	v_mfma_f32_16x16x32_bf16 v[116:119], v[214:217], v[152:155], v[116:119]
	v_mfma_f32_16x16x32_bf16 v[112:115], v[236:239], v[152:155], v[112:115]
	v_mfma_f32_16x16x32_bf16 v[100:103], v[214:217], v[160:163], v[100:103]
	v_mfma_f32_16x16x32_bf16 v[96:99], v[236:239], v[160:163], v[96:99]
	v_mfma_f32_16x16x32_bf16 v[76:79], v[214:217], v[168:171], v[76:79]
	v_mfma_f32_16x16x32_bf16 v[72:75], v[236:239], v[168:171], v[72:75]
	v_mfma_f32_16x16x32_bf16 v[124:127], v[218:221], v[148:151], v[124:127]
	v_mfma_f32_16x16x32_bf16 v[120:123], v[240:243], v[148:151], v[120:123]
	v_mfma_f32_16x16x32_bf16 v[116:119], v[218:221], v[156:159], v[116:119]
	v_mfma_f32_16x16x32_bf16 v[112:115], v[240:243], v[156:159], v[112:115]
	v_mfma_f32_16x16x32_bf16 v[100:103], v[218:221], v[164:167], v[100:103]
	v_mfma_f32_16x16x32_bf16 v[96:99], v[240:243], v[164:167], v[96:99]
	v_mfma_f32_16x16x32_bf16 v[76:79], v[218:221], v[210:213], v[76:79]
	v_mfma_f32_16x16x32_bf16 v[72:75], v[240:243], v[210:213], v[72:75]
	s_mov_b32 m0, s74
	v_lshl_add_u64 v[248:249], s[4:5], 0, v[182:183]
	s_barrier
	ds_read_b128 v[144:147], v235 offset:16384
	ds_read_b128 v[148:151], v235 offset:17408
	ds_read_b128 v[152:155], v235 offset:18432
	ds_read_b128 v[156:159], v235 offset:19456
	ds_read_b128 v[160:163], v235 offset:20480
	ds_read_b128 v[164:167], v235 offset:21504
	ds_read_b128 v[168:171], v235 offset:22528
	ds_read_b128 v[210:213], v235 offset:23552
	global_load_lds_dwordx4 v[248:249], off
	v_lshl_add_u64 v[250:251], s[4:5], 0, v[186:187]
	s_mov_b32 m0, s56
	s_nop 0
	global_load_lds_dwordx4 v[250:251], off
	s_barrier
	s_waitcnt lgkmcnt(0)
	s_waitcnt lgkmcnt(0)
	v_mfma_f32_16x16x32_bf16 v[52:55], v[128:131], v[144:147], v[52:55]
	v_mfma_f32_16x16x32_bf16 v[48:51], v[136:139], v[144:147], v[48:51]
	v_mfma_f32_16x16x32_bf16 v[28:31], v[128:131], v[152:155], v[28:31]
	v_mfma_f32_16x16x32_bf16 v[24:27], v[136:139], v[152:155], v[24:27]
	v_mfma_f32_16x16x32_bf16 v[12:15], v[128:131], v[160:163], v[12:15]
	v_mfma_f32_16x16x32_bf16 v[8:11], v[136:139], v[160:163], v[8:11]
	v_mfma_f32_16x16x32_bf16 v[4:7], v[128:131], v[168:171], v[4:7]
	v_mfma_f32_16x16x32_bf16 v[0:3], v[136:139], v[168:171], v[0:3]
	v_mfma_f32_16x16x32_bf16 v[52:55], v[132:135], v[148:151], v[52:55]
	v_mfma_f32_16x16x32_bf16 v[48:51], v[140:143], v[148:151], v[48:51]
	v_mfma_f32_16x16x32_bf16 v[28:31], v[132:135], v[156:159], v[28:31]
	v_mfma_f32_16x16x32_bf16 v[24:27], v[140:143], v[156:159], v[24:27]
	v_mfma_f32_16x16x32_bf16 v[12:15], v[132:135], v[164:167], v[12:15]
	v_mfma_f32_16x16x32_bf16 v[8:11], v[140:143], v[164:167], v[8:11]
	v_mfma_f32_16x16x32_bf16 v[4:7], v[132:135], v[210:213], v[4:7]
	v_mfma_f32_16x16x32_bf16 v[0:3], v[140:143], v[210:213], v[0:3]
	s_barrier
	s_add_u32 s8, s8, s78
	s_addc_u32 s9, s9, 0
	s_add_i32 s45, s3, s97
	v_lshl_add_u64 v[252:253], s[8:9], 0, v[184:185]
	s_mov_b32 m0, s45
	v_lshl_add_u64 v[230:231], s[8:9], 0, v[188:189]
	global_load_lds_dwordx4 v[252:253], off
	s_add_i32 m0, s45, 0x2000
	s_nop 0
	global_load_lds_dwordx4 v[230:231], off
	s_waitcnt vmcnt(6)
	s_barrier
	s_add_i32 s8, 0, 0x18000
	v_add_u32_e32 v140, s8, v234
	v_mfma_f32_16x16x32_bf16 v[88:91], v[214:217], v[144:147], v[88:91]
	ds_read_b128 v[128:131], v140
	v_mfma_f32_16x16x32_bf16 v[84:87], v[236:239], v[144:147], v[84:87]
	ds_read_b128 v[132:135], v140 offset:1024
	v_mfma_f32_16x16x32_bf16 v[64:67], v[214:217], v[152:155], v[64:67]
	ds_read_b128 v[136:139], v140 offset:2048
	v_mfma_f32_16x16x32_bf16 v[60:63], v[236:239], v[152:155], v[60:63]
	ds_read_b128 v[140:143], v140 offset:3072
	v_mfma_f32_16x16x32_bf16 v[40:43], v[214:217], v[160:163], v[40:43]
	v_mfma_f32_16x16x32_bf16 v[36:39], v[236:239], v[160:163], v[36:39]
	v_mfma_f32_16x16x32_bf16 v[20:23], v[214:217], v[168:171], v[20:23]
	v_mfma_f32_16x16x32_bf16 v[16:19], v[236:239], v[168:171], v[16:19]
	v_mfma_f32_16x16x32_bf16 v[88:91], v[218:221], v[148:151], v[88:91]
	v_mfma_f32_16x16x32_bf16 v[84:87], v[240:243], v[148:151], v[84:87]
	v_mfma_f32_16x16x32_bf16 v[64:67], v[218:221], v[156:159], v[64:67]
	v_mfma_f32_16x16x32_bf16 v[60:63], v[240:243], v[156:159], v[60:63]
	v_mfma_f32_16x16x32_bf16 v[40:43], v[218:221], v[164:167], v[40:43]
	v_mfma_f32_16x16x32_bf16 v[36:39], v[240:243], v[164:167], v[36:39]
	v_mfma_f32_16x16x32_bf16 v[20:23], v[218:221], v[210:213], v[20:23]
	v_mfma_f32_16x16x32_bf16 v[16:19], v[240:243], v[210:213], v[16:19]
	s_barrier
	s_add_u32 s4, s4, s60
	s_addc_u32 s5, s5, 0
	s_mov_b32 m0, s57
	v_lshl_add_u64 v[214:215], s[4:5], 0, v[182:183]
	ds_read_b128 v[144:147], v235 offset:32768
	ds_read_b128 v[148:151], v235 offset:33792
	ds_read_b128 v[152:155], v235 offset:34816
	ds_read_b128 v[156:159], v235 offset:35840
	ds_read_b128 v[160:163], v235 offset:36864
	ds_read_b128 v[164:167], v235 offset:37888
	ds_read_b128 v[168:171], v235 offset:38912
	ds_read_b128 v[210:213], v235 offset:39936
	global_load_lds_dwordx4 v[214:215], off
	v_lshl_add_u64 v[214:215], s[4:5], 0, v[186:187]
	s_mov_b32 m0, s68
	s_nop 0
	global_load_lds_dwordx4 v[214:215], off
	s_waitcnt lgkmcnt(8)
	s_barrier
	s_waitcnt lgkmcnt(0)
	s_waitcnt lgkmcnt(0)
	v_mfma_f32_16x16x32_bf16 v[108:111], v[128:131], v[144:147], v[108:111]
	v_mfma_f32_16x16x32_bf16 v[104:107], v[136:139], v[144:147], v[104:107]
	v_mfma_f32_16x16x32_bf16 v[92:95], v[128:131], v[152:155], v[92:95]
	v_mfma_f32_16x16x32_bf16 v[80:83], v[136:139], v[152:155], v[80:83]
	v_mfma_f32_16x16x32_bf16 v[68:71], v[128:131], v[160:163], v[68:71]
	v_mfma_f32_16x16x32_bf16 v[56:59], v[136:139], v[160:163], v[56:59]
	v_mfma_f32_16x16x32_bf16 v[44:47], v[128:131], v[168:171], v[44:47]
	v_mfma_f32_16x16x32_bf16 v[32:35], v[136:139], v[168:171], v[32:35]
	v_mfma_f32_16x16x32_bf16 v[108:111], v[132:135], v[148:151], v[108:111]
	v_mfma_f32_16x16x32_bf16 v[104:107], v[140:143], v[148:151], v[104:107]
	v_mfma_f32_16x16x32_bf16 v[92:95], v[132:135], v[156:159], v[92:95]
	v_mfma_f32_16x16x32_bf16 v[80:83], v[140:143], v[156:159], v[80:83]
	v_mfma_f32_16x16x32_bf16 v[68:71], v[132:135], v[164:167], v[68:71]
	v_mfma_f32_16x16x32_bf16 v[56:59], v[140:143], v[164:167], v[56:59]
	v_mfma_f32_16x16x32_bf16 v[44:47], v[132:135], v[210:213], v[44:47]
	v_mfma_f32_16x16x32_bf16 v[32:35], v[140:143], v[210:213], v[32:35]
	s_barrier
	s_add_i32 s4, 0, 0x1c000
	s_add_i32 s5, s8, s97
	v_add_u32_e32 v172, s4, v234
	v_lshl_add_u64 v[244:245], v[244:245], 0, s[54:55]
	s_mov_b32 m0, s5
	ds_read_b128 v[214:217], v172
	ds_read_b128 v[218:221], v172 offset:1024
	ds_read_b128 v[236:239], v172 offset:2048
	ds_read_b128 v[240:243], v172 offset:3072
	global_load_lds_dwordx4 v[244:245], off
	v_lshl_add_u64 v[244:245], v[246:247], 0, s[54:55]
	s_add_i32 m0, s5, 0x2000
	s_nop 0
	global_load_lds_dwordx4 v[244:245], off
	s_barrier
	s_waitcnt lgkmcnt(0)
	s_waitcnt lgkmcnt(0)
	v_mfma_f32_16x16x32_bf16 v[124:127], v[214:217], v[144:147], v[124:127]
	v_mfma_f32_16x16x32_bf16 v[120:123], v[236:239], v[144:147], v[120:123]
	v_mfma_f32_16x16x32_bf16 v[116:119], v[214:217], v[152:155], v[116:119]
	v_mfma_f32_16x16x32_bf16 v[112:115], v[236:239], v[152:155], v[112:115]
	v_mfma_f32_16x16x32_bf16 v[100:103], v[214:217], v[160:163], v[100:103]
	v_mfma_f32_16x16x32_bf16 v[96:99], v[236:239], v[160:163], v[96:99]
	v_mfma_f32_16x16x32_bf16 v[76:79], v[214:217], v[168:171], v[76:79]
	v_mfma_f32_16x16x32_bf16 v[72:75], v[236:239], v[168:171], v[72:75]
	v_mfma_f32_16x16x32_bf16 v[124:127], v[218:221], v[148:151], v[124:127]
	v_mfma_f32_16x16x32_bf16 v[120:123], v[240:243], v[148:151], v[120:123]
	v_mfma_f32_16x16x32_bf16 v[116:119], v[218:221], v[156:159], v[116:119]
	v_mfma_f32_16x16x32_bf16 v[112:115], v[240:243], v[156:159], v[112:115]
	v_mfma_f32_16x16x32_bf16 v[100:103], v[218:221], v[164:167], v[100:103]
	v_mfma_f32_16x16x32_bf16 v[96:99], v[240:243], v[164:167], v[96:99]
	v_mfma_f32_16x16x32_bf16 v[76:79], v[218:221], v[210:213], v[76:79]
	v_mfma_f32_16x16x32_bf16 v[72:75], v[240:243], v[210:213], v[72:75]
	s_mov_b32 m0, s69
	v_lshl_add_u64 v[244:245], v[248:249], 0, s[54:55]
	s_barrier
	ds_read_b128 v[144:147], v235 offset:49152
	ds_read_b128 v[148:151], v235 offset:50176
	ds_read_b128 v[152:155], v235 offset:51200
	ds_read_b128 v[156:159], v235 offset:52224
	ds_read_b128 v[160:163], v235 offset:53248
	ds_read_b128 v[164:167], v235 offset:54272
	ds_read_b128 v[168:171], v235 offset:55296
	ds_read_b128 v[210:213], v235 offset:56320
	global_load_lds_dwordx4 v[244:245], off
	v_lshl_add_u64 v[244:245], v[250:251], 0, s[54:55]
	s_mov_b32 m0, s26
	s_nop 0
	global_load_lds_dwordx4 v[244:245], off
	s_barrier
	s_waitcnt lgkmcnt(0)
	s_waitcnt lgkmcnt(0)
	v_mfma_f32_16x16x32_bf16 v[52:55], v[128:131], v[144:147], v[52:55]
	v_mfma_f32_16x16x32_bf16 v[48:51], v[136:139], v[144:147], v[48:51]
	v_mfma_f32_16x16x32_bf16 v[28:31], v[128:131], v[152:155], v[28:31]
	v_mfma_f32_16x16x32_bf16 v[24:27], v[136:139], v[152:155], v[24:27]
	v_mfma_f32_16x16x32_bf16 v[12:15], v[128:131], v[160:163], v[12:15]
	v_mfma_f32_16x16x32_bf16 v[8:11], v[136:139], v[160:163], v[8:11]
	v_mfma_f32_16x16x32_bf16 v[4:7], v[128:131], v[168:171], v[4:7]
	v_mfma_f32_16x16x32_bf16 v[0:3], v[136:139], v[168:171], v[0:3]
	v_mfma_f32_16x16x32_bf16 v[52:55], v[132:135], v[148:151], v[52:55]
	v_mfma_f32_16x16x32_bf16 v[48:51], v[140:143], v[148:151], v[48:51]
	v_mfma_f32_16x16x32_bf16 v[28:31], v[132:135], v[156:159], v[28:31]
	v_mfma_f32_16x16x32_bf16 v[24:27], v[140:143], v[156:159], v[24:27]
	v_mfma_f32_16x16x32_bf16 v[12:15], v[132:135], v[164:167], v[12:15]
	v_mfma_f32_16x16x32_bf16 v[8:11], v[140:143], v[164:167], v[8:11]
	v_mfma_f32_16x16x32_bf16 v[4:7], v[132:135], v[210:213], v[4:7]
	v_mfma_f32_16x16x32_bf16 v[0:3], v[140:143], v[210:213], v[0:3]
	s_barrier
	s_add_i32 s4, s4, s97
	v_lshl_add_u64 v[128:129], v[252:253], 0, s[54:55]
	s_mov_b32 m0, s4
	s_nop 0
	global_load_lds_dwordx4 v[128:129], off
	v_lshl_add_u64 v[128:129], v[230:231], 0, s[54:55]
	s_add_i32 m0, s4, 0x2000
	s_nop 0
	global_load_lds_dwordx4 v[128:129], off
	s_waitcnt vmcnt(6)
	s_barrier
	v_mfma_f32_16x16x32_bf16 v[88:91], v[214:217], v[144:147], v[88:91]
	v_mfma_f32_16x16x32_bf16 v[84:87], v[236:239], v[144:147], v[84:87]
	v_mfma_f32_16x16x32_bf16 v[64:67], v[214:217], v[152:155], v[64:67]
	v_mfma_f32_16x16x32_bf16 v[60:63], v[236:239], v[152:155], v[60:63]
	v_mfma_f32_16x16x32_bf16 v[40:43], v[214:217], v[160:163], v[40:43]
	v_mfma_f32_16x16x32_bf16 v[36:39], v[236:239], v[160:163], v[36:39]
	v_mfma_f32_16x16x32_bf16 v[20:23], v[214:217], v[168:171], v[20:23]
	v_mfma_f32_16x16x32_bf16 v[16:19], v[236:239], v[168:171], v[16:19]
	v_mfma_f32_16x16x32_bf16 v[88:91], v[218:221], v[148:151], v[88:91]
	v_mfma_f32_16x16x32_bf16 v[84:87], v[240:243], v[148:151], v[84:87]
	v_mfma_f32_16x16x32_bf16 v[64:67], v[218:221], v[156:159], v[64:67]
	v_mfma_f32_16x16x32_bf16 v[60:63], v[240:243], v[156:159], v[60:63]
	v_mfma_f32_16x16x32_bf16 v[40:43], v[218:221], v[164:167], v[40:43]
	v_mfma_f32_16x16x32_bf16 v[36:39], v[240:243], v[164:167], v[36:39]
	v_mfma_f32_16x16x32_bf16 v[20:23], v[218:221], v[210:213], v[20:23]
	v_mfma_f32_16x16x32_bf16 v[16:19], v[240:243], v[210:213], v[16:19]
	s_add_u32 s6, s6, 0x100
	s_addc_u32 s7, s7, 0
	s_add_u32 s42, s42, 0x100
	s_addc_u32 s43, s43, 0
	s_cmp_ge_u32 s44, s73
	s_mov_b32 s4, s44
	s_barrier
	s_cbranch_scc0 .LBB0_744
	s_lshl_b32 s52, s30, 8
	s_cmp_lt_i32 s96, 2
	s_mov_b64 s[4:5], -1
	s_cbranch_scc1 .LBB0_898
	s_cmp_gt_i32 s96, 2
	s_cbranch_scc0 .LBB0_895
	s_add_i32 s30, s52, s82
	v_or_b32_e32 v210, s30, v179
	s_and_b32 s4, s10, -4
	s_cmp_lg_u32 s4, 4
	s_movk_i32 s4, 0x2000
	s_movk_i32 s6, 0x1fff
	v_or_b32_e32 v212, 16, v210
	v_cmp_gt_i32_e32 vcc, s4, v210
	v_cmp_lt_i32_e64 s[42:43], s6, v210
	s_mov_b64 s[4:5], -1
	v_ashrrev_i32_e32 v211, 31, v210
	s_movk_i32 s53, 0x1fff
	v_cmp_lt_i32_e64 s[46:47], s6, v212
	s_cbranch_scc0 .LBB0_829
	v_lshlrev_b32_e32 v128, 6, v212
	s_movk_i32 s4, 0x2000
	v_and_b32_e32 v128, 0x3f7c0, v128
	v_cmp_gt_i32_e64 s[44:45], s4, v212
	v_lshlrev_b32_e32 v219, 6, v210
	v_and_b32_e32 v144, 0x3f3c0, v219
	v_cndmask_b32_e64 v128, v225, v128, s[44:45]
	v_lshlrev_b32_e32 v172, 2, v128
	v_cndmask_b32_e32 v144, v225, v144, vcc
	v_lshl_add_u64 v[132:133], v[196:197], 0, v[172:173]
	v_lshl_add_u64 v[140:141], v[198:199], 0, v[172:173]
	v_lshlrev_b32_e32 v172, 2, v144
	v_lshl_add_u64 v[144:145], v[198:199], 0, v[172:173]
	global_load_dwordx4 v[128:131], v[132:133], off offset:16
	global_load_dwordx4 v[136:139], v[132:133], off
	s_nop 0
	global_load_dwordx4 v[132:135], v[140:141], off offset:16
	s_nop 0
	global_load_dwordx4 v[140:143], v[140:141], off
	s_nop 0
	global_load_dwordx4 v[156:159], v[144:145], off offset:16
	global_load_dwordx4 v[152:155], v[144:145], off
	v_lshl_add_u64 v[144:145], v[196:197], 0, v[172:173]
	global_load_dwordx4 v[160:163], v[144:145], off offset:16
	global_load_dwordx4 v[164:167], v[144:145], off
	s_cmp_gt_i32 s10, 3
	s_cselect_b64 s[4:5], -1, 0
	s_lshl_b32 s6, s10, 1
	s_add_i32 s7, s6, -16
	s_cmp_lt_i32 s10, 4
	s_cselect_b32 s6, s6, s7
	v_readlane_b32 s7, v255, 50
	s_or_b32 s6, s6, s7
	s_lshl_b32 s94, s6, 7
	s_ashr_i32 s95, s94, 31
	s_lshl_b64 s[6:7], s[94:95], 1
	v_lshl_add_u64 v[214:215], v[200:201], 0, s[6:7]
	s_waitcnt vmcnt(0)
	v_pk_mul_f32 v[144:145], v[126:127], v[154:155]
	v_pk_mul_f32 v[148:149], v[124:125], v[152:153]
	v_pk_fma_f32 v[146:147], v[110:111], v[166:167], v[144:145] neg_lo:[0,0,1] neg_hi:[0,0,1]
	v_pk_fma_f32 v[144:145], v[108:109], v[164:165], v[148:149] neg_lo:[0,0,1] neg_hi:[0,0,1]
	v_pk_mul_f32 v[148:149], v[122:123], v[158:159]
	v_pk_mul_f32 v[168:169], v[120:121], v[156:157]
	v_pk_fma_f32 v[150:151], v[106:107], v[162:163], v[148:149] neg_lo:[0,0,1] neg_hi:[0,0,1]
	v_pk_fma_f32 v[148:149], v[104:105], v[160:161], v[168:169] neg_lo:[0,0,1] neg_hi:[0,0,1]
	v_pk_mul_f32 v[166:167], v[126:127], v[166:167]
	v_pk_mul_f32 v[164:165], v[124:125], v[164:165]
	v_pk_mul_f32 v[162:163], v[122:123], v[162:163]
	v_pk_mul_f32 v[160:161], v[120:121], v[160:161]
	v_pk_fma_f32 v[154:155], v[110:111], v[154:155], v[166:167]
	v_pk_fma_f32 v[152:153], v[108:109], v[152:153], v[164:165]
	v_pk_fma_f32 v[158:159], v[106:107], v[158:159], v[162:163]
	v_pk_fma_f32 v[156:157], v[104:105], v[156:157], v[160:161]
	v_cvt_pk_bf16_f32 v160, v144, v145
	v_cvt_pk_bf16_f32 v161, v146, v147
	v_cvt_pk_bf16_f32 v162, v148, v149
	v_cvt_pk_bf16_f32 v163, v150, v151
	v_cvt_pk_bf16_f32 v164, v152, v153
	v_cvt_pk_bf16_f32 v165, v154, v155
	v_cvt_pk_bf16_f32 v166, v156, v157
	v_cvt_pk_bf16_f32 v167, v158, v159
	s_mov_b64 s[8:9], -1
	s_and_b64 vcc, exec, s[4:5]
	s_cbranch_vccz .LBB0_750
	s_movk_i32 s8, 0x1800
	v_mad_i64_i32 v[168:169], s[8:9], v210, s8, v[214:215]
	global_store_dwordx4 v[168:169], v[160:163], off
	global_store_dwordx4 v[168:169], v[164:167], off offset:128
	s_mov_b64 s[8:9], 0
